# v30 plus non-temporal cache policy on the proj/wo epilogue stores and the final f32 output stores
# speedup vs baseline: 1.0201x; 1.0033x over previous
;   DI u16* qbuf() const { return (u16*)(ws + OFF_qbuf); }
;   DI u16* kbuf() const { return (u16*)(ws + OFF_kbuf); }
;   DI u16* vtbuf() const { return (u16*)(ws + OFF_vtbuf); }
; DI void phase_proj(const Params& p, int layer, u16* lds, const int WAVE_S) {
;     ...
;     {
;       const int token0 = tt * 128 + wj0;
;       const int b = token0 >> 11, s0 = token0 & 2047;
;       u16* dst;
;       size_t rstride;
;       if (type == 2) { dst = p.vtbuf() + ((size_t)(grp * 32 + b) * 2 + head) * 64 * SEQ + s0; rstride = SEQ; }
;       else if (type == 0) { dst = p.qbuf() + (((size_t)(grp * 32 + b) * 8 + head) * SEQ + s0) * 64; rstride = 64; }
;       else { dst = p.kbuf() + (((size_t)(grp * 32 + b) * 2 + head) * SEQ + s0) * 64; rstride = 64; }
; #pragma unroll
;       for (int it = 0; it < 8; ++it) {
;         const int row = it * 8 + (lane >> 3), ch = lane & 7;
;         *(u32x4*)(dst + (size_t)row * rstride + ch * 8) = *(const u32x4*)(wl + row * LSTR + ch * 8);
;       }
.LBB0_70:
	v_lshl_add_u64 v[6:7], v[2:3], 0, v[0:1]
	ds_read_b128 v[2:5], v141
	v_mul_u32_u24_e32 v8, s18, v130
	v_lshlrev_b32_e32 v8, 1, v8
	v_mov_b32_e32 v9, v1
	v_lshl_add_u64 v[8:9], v[6:7], 0, v[8:9]
	s_waitcnt lgkmcnt(0)
	global_store_dwordx4 v[8:9], v[2:5], off nt
	ds_read_b128 v[2:5], v141 offset:1152
	v_mul_u32_u24_e32 v8, s18, v134
	v_lshlrev_b32_e32 v8, 1, v8
	v_mov_b32_e32 v9, v1
	v_lshl_add_u64 v[8:9], v[6:7], 0, v[8:9]
	s_waitcnt lgkmcnt(0)
	global_store_dwordx4 v[8:9], v[2:5], off nt
	ds_read_b128 v[2:5], v141 offset:2304
	v_mul_u32_u24_e32 v8, s18, v135
	v_lshlrev_b32_e32 v8, 1, v8
	v_mov_b32_e32 v9, v1
	v_lshl_add_u64 v[8:9], v[6:7], 0, v[8:9]
	s_waitcnt lgkmcnt(0)
	global_store_dwordx4 v[8:9], v[2:5], off nt
	ds_read_b128 v[2:5], v141 offset:3456
	v_mul_u32_u24_e32 v8, s18, v136
	v_lshlrev_b32_e32 v8, 1, v8
	v_mov_b32_e32 v9, v1
	v_lshl_add_u64 v[8:9], v[6:7], 0, v[8:9]
	s_waitcnt lgkmcnt(0)
	global_store_dwordx4 v[8:9], v[2:5], off nt
	ds_read_b128 v[2:5], v141 offset:4608
	v_mul_u32_u24_e32 v8, s18, v137
	v_lshlrev_b32_e32 v8, 1, v8
	v_mov_b32_e32 v9, v1
	v_lshl_add_u64 v[8:9], v[6:7], 0, v[8:9]
	s_waitcnt lgkmcnt(0)
	global_store_dwordx4 v[8:9], v[2:5], off nt
	ds_read_b128 v[2:5], v141 offset:5760
	v_mul_u32_u24_e32 v8, s18, v138
	v_lshlrev_b32_e32 v8, 1, v8
	v_mov_b32_e32 v9, v1
	v_lshl_add_u64 v[8:9], v[6:7], 0, v[8:9]
	s_waitcnt lgkmcnt(0)
	global_store_dwordx4 v[8:9], v[2:5], off nt
	ds_read_b128 v[2:5], v141 offset:6912
	v_mul_u32_u24_e32 v8, s18, v139
	v_lshlrev_b32_e32 v8, 1, v8
	v_mov_b32_e32 v9, v1
	v_lshl_add_u64 v[8:9], v[6:7], 0, v[8:9]
	s_waitcnt lgkmcnt(0)
	global_store_dwordx4 v[8:9], v[2:5], off nt
	ds_read_b128 v[2:5], v141 offset:8064
	v_mul_u32_u24_e32 v8, s18, v140
	v_lshlrev_b32_e32 v8, 1, v8
	v_mov_b32_e32 v9, v1
	v_lshl_add_u64 v[6:7], v[6:7], 0, v[8:9]
	s_mov_b64 s[18:19], 0
	s_waitcnt lgkmcnt(0)
	global_store_dwordx4 v[6:7], v[2:5], off nt

; #define MFMA32(a, b, c) __builtin_amdgcn_mfma_f32_32x32x16_bf16((a), (b), (c), 0, 0, 0)
;     ...
;   for (int kt = 0; kt < NKT; ++kt) {
;     __syncthreads();
; #pragma unroll
;     for (int it = 0; it < 4; ++it) {
;       *(u32x4*)(Xs + (lr + 32 * it) * LSTR + lc) = xr[it];
;       *(u32x4*)(Ys + (lr + 32 * it) * LSTR + lc) = yr[it];
;     }
;     __syncthreads();
;     if (kt + 1 < NKT) {
; #pragma unroll
;       for (int it = 0; it < 4; ++it) {
;         xr[it] = *(const u32x4*)(xg + (size_t)it * 32 * RS + (kt + 1) * 64);
;         yr[it] = *(const u32x4*)(yg + (size_t)it * 32 * RS + (kt + 1) * 64);
;       }
;     }
; #pragma unroll
;     for (int ks = 0; ks < 4; ++ks) {
;       bf16x8 af[TI], bfr[TJ];
; #pragma unroll
;       for (int a = 0; a < TI; ++a) af[a] = *(const bf16x8*)(Xs + (wi0 + a * 32 + fr) * LSTR + ks * 16 + fh);
; #pragma unroll
;       for (int b = 0; b < TJ; ++b) bfr[b] = *(const bf16x8*)(Ys + (wj0 + b * 32 + fr) * LSTR + ks * 16 + fh);
; #pragma unroll
;       for (int a = 0; a < TI; ++a)
; #pragma unroll
;         for (int b = 0; b < TJ; ++b) acc[a][b] = MFMA32(af[a], bfr[b], acc[a][b]);
;     }
;     __builtin_amdgcn_iglp_opt(1);
;   }
.LBB0_260:
	s_barrier
	s_waitcnt vmcnt(7)
	ds_write_b128 v118, v[66:69]
	s_waitcnt vmcnt(6)
	ds_write_b128 v118, v[70:73] offset:18432
	s_waitcnt vmcnt(5)
	ds_write_b128 v118, v[74:77] offset:4608
	s_waitcnt vmcnt(4)
	ds_write_b128 v118, v[78:81] offset:23040
	s_waitcnt vmcnt(3)
	ds_write_b128 v118, v[82:85] offset:9216
	s_waitcnt vmcnt(2)
	ds_write_b128 v118, v[86:89] offset:27648
	s_waitcnt vmcnt(1)
	ds_write_b128 v118, v[90:93] offset:13824
	s_waitcnt vmcnt(0)
	ds_write_b128 v118, v[94:97] offset:32256
	s_waitcnt lgkmcnt(0)
	s_barrier
	ds_read_b128 v[128:131], v101 offset:4608
	ds_read_b128 v[136:139], v101
	ds_read_b128 v[132:135], v0 offset:23040
	ds_read_b128 v[148:151], v0 offset:18432
	ds_read_b128 v[140:143], v101 offset:32
	ds_read_b128 v[152:155], v0 offset:18464
	s_waitcnt lgkmcnt(2)
	v_mfma_f32_32x32x16_bf16 v[34:49], v[128:131], v[148:151], v[34:49]
	v_lshl_add_u64 v[90:91], v[120:121], 0, s[44:45]
	s_mov_b32 s19, 0x33680000
	v_add_co_u32_e32 v66, vcc, s19, v90
	v_lshl_add_u64 v[94:95], v[122:123], 0, s[44:45]
	s_nop 0
	v_addc_co_u32_e32 v67, vcc, 0, v91, vcc
	v_mfma_f32_32x32x16_bf16 v[2:17], v[128:131], v[132:135], v[2:17]
	ds_read_b128 v[128:131], v101 offset:4640
	v_add_co_u32_e32 v70, vcc, s91, v94
	s_mov_b32 s19, 0x33690000
	s_nop 0
	v_addc_co_u32_e32 v71, vcc, 0, v95, vcc
	v_add_co_u32_e32 v74, vcc, s19, v90
	v_mfma_f32_32x32x16_bf16 v[18:33], v[136:139], v[132:135], v[18:33]
	ds_read_b128 v[132:135], v0 offset:23072
	v_addc_co_u32_e32 v75, vcc, 0, v91, vcc
	s_mov_b32 s19, 0x14010000
	v_add_co_u32_e32 v78, vcc, s19, v94
	s_mov_b32 s19, 0x336a0000
	s_waitcnt lgkmcnt(1)
	v_mfma_f32_32x32x16_bf16 v[34:49], v[128:131], v[152:155], v[34:49]
	v_addc_co_u32_e32 v79, vcc, 0, v95, vcc
	v_add_co_u32_e32 v82, vcc, s19, v90
	s_mov_b32 s19, 0x14020000
	s_nop 0
	v_addc_co_u32_e32 v83, vcc, 0, v91, vcc
	s_waitcnt lgkmcnt(0)
	v_mfma_f32_32x32x16_bf16 v[2:17], v[128:131], v[132:135], v[2:17]
	ds_read_b128 v[128:131], v101 offset:64
	v_add_co_u32_e32 v86, vcc, s19, v94
	s_mov_b32 s19, 0x336b0000
	s_nop 0
	v_addc_co_u32_e32 v87, vcc, 0, v95, vcc
	v_add_co_u32_e32 v90, vcc, s19, v90
	v_mfma_f32_32x32x16_bf16 v[18:33], v[140:143], v[132:135], v[18:33]
	ds_read_b128 v[132:135], v101 offset:4672
	v_addc_co_u32_e32 v91, vcc, 0, v91, vcc
	s_mov_b32 s19, 0x14030000
	v_add_co_u32_e32 v94, vcc, s19, v94
	s_add_u32 s44, s44, 0x80
	v_mfma_f32_32x32x16_bf16 v[50:65], v[136:139], v[148:151], v[50:65]
	ds_read_b128 v[136:139], v0 offset:18496
	v_addc_co_u32_e32 v95, vcc, 0, v95, vcc
	s_addc_u32 s45, s45, 0
	s_cmpk_lg_i32 s44, 0x780
	v_mfma_f32_32x32x16_bf16 v[50:65], v[140:143], v[152:155], v[50:65]
	ds_read_b128 v[140:143], v0 offset:23104
	s_waitcnt lgkmcnt(1)
	v_mfma_f32_32x32x16_bf16 v[50:65], v[128:131], v[136:139], v[50:65]
	s_waitcnt lgkmcnt(0)
	v_mfma_f32_32x32x16_bf16 v[18:33], v[128:131], v[140:143], v[18:33]
	ds_read_b128 v[128:131], v101 offset:96
	v_mfma_f32_32x32x16_bf16 v[34:49], v[132:135], v[136:139], v[34:49]
	v_mfma_f32_32x32x16_bf16 v[2:17], v[132:135], v[140:143], v[2:17]
	ds_read_b128 v[132:135], v101 offset:4704
	ds_read_b128 v[136:139], v0 offset:18528
	ds_read_b128 v[140:143], v0 offset:23136
	global_load_dwordx4 v[66:69], v[66:67], off offset:128
	s_nop 0
	global_load_dwordx4 v[70:73], v[70:71], off offset:128
	s_nop 0
	global_load_dwordx4 v[74:77], v[74:75], off offset:128
	s_nop 0
	global_load_dwordx4 v[78:81], v[78:79], off offset:128
	s_nop 0
	global_load_dwordx4 v[82:85], v[82:83], off offset:128
	s_nop 0
	global_load_dwordx4 v[86:89], v[86:87], off offset:128
	s_nop 0
	global_load_dwordx4 v[90:93], v[90:91], off offset:128
	s_nop 0
	global_load_dwordx4 v[94:97], v[94:95], off offset:128
	s_waitcnt lgkmcnt(1)
	v_mfma_f32_32x32x16_bf16 v[50:65], v[128:131], v[136:139], v[50:65]
	s_waitcnt lgkmcnt(0)
	v_mfma_f32_32x32x16_bf16 v[18:33], v[128:131], v[140:143], v[18:33]
	v_mfma_f32_32x32x16_bf16 v[34:49], v[132:135], v[136:139], v[34:49]
	v_mfma_f32_32x32x16_bf16 v[2:17], v[132:135], v[140:143], v[2:17]
	s_cbranch_scc1 .LBB0_260
	s_barrier
	s_waitcnt vmcnt(7)
	ds_write_b128 v118, v[66:69]
	s_waitcnt vmcnt(6)
	ds_write_b128 v118, v[70:73] offset:18432
	s_waitcnt vmcnt(5)
	ds_write_b128 v118, v[74:77] offset:4608
	s_waitcnt vmcnt(4)
	ds_write_b128 v118, v[78:81] offset:23040
	s_waitcnt vmcnt(3)
	ds_write_b128 v118, v[82:85] offset:9216
	s_waitcnt vmcnt(2)
	ds_write_b128 v118, v[86:89] offset:27648
	s_waitcnt vmcnt(1)
	ds_write_b128 v118, v[90:93] offset:13824
	s_waitcnt vmcnt(0)
	ds_write_b128 v118, v[94:97] offset:32256
	s_waitcnt lgkmcnt(0)
	s_barrier
; #define MFMA32(a, b, c) __builtin_amdgcn_mfma_f32_32x32x16_bf16((a), (b), (c), 0, 0, 0)
;   DI u16* yb() const { return (u16*)(ws + OFF_yb); }
;     ...
;     for (int ks = 0; ks < 4; ++ks) {
;       bf16x8 af[TI], bfr[TJ];
; #pragma unroll
;       for (int a = 0; a < TI; ++a) af[a] = *(const bf16x8*)(Xs + (wi0 + a * 32 + fr) * LSTR + ks * 16 + fh);
; #pragma unroll
;       for (int b = 0; b < TJ; ++b) bfr[b] = *(const bf16x8*)(Ys + (wj0 + b * 32 + fr) * LSTR + ks * 16 + fh);
; #pragma unroll
;       for (int a = 0; a < TI; ++a)
; #pragma unroll
;         for (int b = 0; b < TJ; ++b) acc[a][b] = MFMA32(af[a], bfr[b], acc[a][b]);
;     }
;     __builtin_amdgcn_iglp_opt(1);
;   }
; DI void phase_wo(const Params& p, int layer, u16* lds, const int WAVE_S) {
;     ...
;     __syncthreads();
;     u16* wl = lds + wave * 64 * LSTR;
; #pragma unroll
;     for (int tj = 0; tj < 2; ++tj)
; #pragma unroll
;       for (int ti = 0; ti < 2; ++ti)
; #pragma unroll
;         for (int g4 = 0; g4 < 4; ++g4)
;           *(uint2*)(wl + (tj * 32 + r) * LSTR + ti * 32 + 8 * g4 + 4 * h) =
;               make_uint2(pk2(acc[ti][tj][4 * g4 + 0], acc[ti][tj][4 * g4 + 1]), pk2(acc[ti][tj][4 * g4 + 2], acc[ti][tj][4 * g4 + 3]));
;     u16* dst = p.yb() + (size_t)(tt * 128 + wj0) * DM + ft * 128 + wi0;
; #pragma unroll
;     for (int it = 0; it < 8; ++it) {
;       const int row = it * 8 + (lane >> 3), ch = lane & 7;
;       *(u32x4*)(dst + (size_t)row * DM + ch * 8) = *(const u32x4*)(wl + row * LSTR + ch * 8);
;     }
	ds_read_b128 v[66:69], v101 offset:4608
	ds_read_b128 v[74:77], v101
	ds_read_b128 v[70:73], v0 offset:23040
	ds_read_b128 v[82:85], v0 offset:18432
	ds_read_b128 v[78:81], v101 offset:32
	ds_read_b128 v[86:89], v0 offset:18464
	s_waitcnt lgkmcnt(2)
	v_mfma_f32_32x32x16_bf16 v[34:49], v[66:69], v[82:85], v[34:49]
	s_lshl_b32 s28, s18, 8
	v_mov_b32_e32 v103, v1
	v_mov_b32_e32 v105, v1
	v_mov_b32_e32 v107, v1
	v_mov_b32_e32 v109, v1
	v_mov_b32_e32 v111, v1
	v_mov_b32_e32 v113, v1
	v_mfma_f32_32x32x16_bf16 v[2:17], v[66:69], v[70:73], v[2:17]
	ds_read_b128 v[66:69], v101 offset:4640
	v_mov_b32_e32 v115, v1
	v_mov_b32_e32 v117, v1
	s_mov_b64 s[18:19], 0
	s_movk_i32 s50, 0x6000
	v_mfma_f32_32x32x16_bf16 v[18:33], v[74:77], v[70:73], v[18:33]
	ds_read_b128 v[70:73], v0 offset:23072
	s_waitcnt lgkmcnt(1)
	v_mfma_f32_32x32x16_bf16 v[34:49], v[66:69], v[86:89], v[34:49]
	s_waitcnt lgkmcnt(0)
	v_mfma_f32_32x32x16_bf16 v[2:17], v[66:69], v[70:73], v[2:17]
	ds_read_b128 v[66:69], v101 offset:64
	v_mfma_f32_32x32x16_bf16 v[18:33], v[78:81], v[70:73], v[18:33]
	ds_read_b128 v[70:73], v101 offset:4672
	v_mfma_f32_32x32x16_bf16 v[50:65], v[74:77], v[82:85], v[50:65]
	ds_read_b128 v[74:77], v0 offset:18496
	v_mfma_f32_32x32x16_bf16 v[50:65], v[78:81], v[86:89], v[50:65]
	ds_read_b128 v[78:81], v0 offset:23104
	s_waitcnt lgkmcnt(1)
	v_mfma_f32_32x32x16_bf16 v[50:65], v[66:69], v[74:77], v[50:65]
	s_waitcnt lgkmcnt(0)
	v_mfma_f32_32x32x16_bf16 v[18:33], v[66:69], v[78:81], v[18:33]
	ds_read_b128 v[66:69], v101 offset:96
	v_mfma_f32_32x32x16_bf16 v[34:49], v[70:73], v[74:77], v[34:49]
	v_mfma_f32_32x32x16_bf16 v[2:17], v[70:73], v[78:81], v[2:17]
	ds_read_b128 v[70:73], v101 offset:4704
	ds_read_b128 v[74:77], v0 offset:18528
	ds_read_b128 v[78:81], v0 offset:23136
	s_waitcnt lgkmcnt(0)
	s_barrier
	v_add_u32_e32 v0, 0x1000, v125
	v_mfma_f32_32x32x16_bf16 v[50:65], v[66:69], v[74:77], v[50:65]
	v_mov_b32_e32 v101, v1
	s_nop 10
	v_cvt_pk_bf16_f32 v50, v50, v51
	v_cvt_pk_bf16_f32 v51, v52, v53
	v_cvt_pk_bf16_f32 v52, v54, v55
	v_cvt_pk_bf16_f32 v53, v56, v57
	ds_write2_b64 v125, v[50:51], v[52:53] offset1:2
	v_cvt_pk_bf16_f32 v50, v58, v59
	v_cvt_pk_bf16_f32 v51, v60, v61
	v_cvt_pk_bf16_f32 v52, v62, v63
	v_cvt_pk_bf16_f32 v53, v64, v65
	v_mfma_f32_32x32x16_bf16 v[18:33], v[66:69], v[78:81], v[18:33]
	ds_write2_b64 v125, v[50:51], v[52:53] offset0:4 offset1:6
	v_mfma_f32_32x32x16_bf16 v[34:49], v[70:73], v[74:77], v[34:49]
	s_nop 9
	v_cvt_pk_bf16_f32 v18, v18, v19
	v_cvt_pk_bf16_f32 v19, v20, v21
	v_cvt_pk_bf16_f32 v20, v22, v23
	v_cvt_pk_bf16_f32 v21, v24, v25
	v_cvt_pk_bf16_f32 v34, v34, v35
	v_cvt_pk_bf16_f32 v35, v36, v37
	v_cvt_pk_bf16_f32 v36, v38, v39
	v_cvt_pk_bf16_f32 v37, v40, v41
	ds_write2_b64 v125, v[34:35], v[36:37] offset0:8 offset1:10
	v_mfma_f32_32x32x16_bf16 v[2:17], v[70:73], v[78:81], v[2:17]
	v_cvt_pk_bf16_f32 v34, v42, v43
	v_cvt_pk_bf16_f32 v35, v44, v45
	v_cvt_pk_bf16_f32 v36, v46, v47
	v_cvt_pk_bf16_f32 v37, v48, v49
	ds_write2_b64 v125, v[34:35], v[36:37] offset0:12 offset1:14
	ds_write2_b64 v0, v[18:19], v[20:21] offset0:64 offset1:66
	v_cvt_pk_bf16_f32 v18, v26, v27
	v_cvt_pk_bf16_f32 v19, v28, v29
	v_cvt_pk_bf16_f32 v20, v30, v31
	v_cvt_pk_bf16_f32 v21, v32, v33
	s_nop 1
	v_cvt_pk_bf16_f32 v2, v2, v3
	v_cvt_pk_bf16_f32 v3, v4, v5
	v_cvt_pk_bf16_f32 v4, v6, v7
	v_cvt_pk_bf16_f32 v5, v8, v9
	ds_write2_b64 v0, v[18:19], v[20:21] offset0:68 offset1:70
	ds_write2_b64 v0, v[2:3], v[4:5] offset0:72 offset1:74
	v_cvt_pk_bf16_f32 v2, v10, v11
	v_cvt_pk_bf16_f32 v3, v12, v13
	v_cvt_pk_bf16_f32 v4, v14, v15
	v_cvt_pk_bf16_f32 v5, v16, v17
	ds_write2_b64 v0, v[2:3], v[4:5] offset0:76 offset1:78
	v_lshl_or_b32 v2, s40, 7, v124
	v_ashrrev_i32_e32 v3, 31, v2
	v_readlane_b32 s40, v165, 58
	v_lshlrev_b64 v[2:3], 11, v[2:3]
	v_readlane_b32 s41, v165, 59
	s_nop 1
	v_lshl_add_u64 v[2:3], s[40:41], 0, v[2:3]
	v_lshl_add_u64 v[2:3], v[2:3], 0, s[28:29]
	v_lshl_add_u64 v[2:3], v[98:99], 1, v[2:3]
	v_lshl_add_u64 v[6:7], v[2:3], 0, v[100:101]
	ds_read_b128 v[2:5], v126
	v_lshl_add_u64 v[8:9], v[6:7], 0, v[102:103]
	s_waitcnt lgkmcnt(0)
	global_store_dwordx4 v[8:9], v[2:5], off nt
	ds_read_b128 v[2:5], v126 offset:1152
	v_lshl_add_u64 v[8:9], v[6:7], 0, v[104:105]
	s_waitcnt lgkmcnt(0)
	global_store_dwordx4 v[8:9], v[2:5], off nt
	ds_read_b128 v[2:5], v126 offset:2304
	v_lshl_add_u64 v[8:9], v[6:7], 0, v[106:107]
	s_waitcnt lgkmcnt(0)
	global_store_dwordx4 v[8:9], v[2:5], off nt
	ds_read_b128 v[2:5], v126 offset:3456
	v_lshl_add_u64 v[8:9], v[6:7], 0, v[108:109]
	s_waitcnt lgkmcnt(0)
	global_store_dwordx4 v[8:9], v[2:5], off nt
	ds_read_b128 v[2:5], v126 offset:4608
	v_lshl_add_u64 v[8:9], v[6:7], 0, v[110:111]
	s_waitcnt lgkmcnt(0)
	global_store_dwordx4 v[8:9], v[2:5], off nt
	ds_read_b128 v[2:5], v126 offset:5760
	v_lshl_add_u64 v[8:9], v[6:7], 0, v[112:113]
	s_waitcnt lgkmcnt(0)
	global_store_dwordx4 v[8:9], v[2:5], off nt
	ds_read_b128 v[2:5], v126 offset:6912
	v_lshl_add_u64 v[8:9], v[6:7], 0, v[114:115]
	v_lshl_add_u64 v[6:7], v[6:7], 0, v[116:117]
	s_waitcnt lgkmcnt(0)
	global_store_dwordx4 v[8:9], v[2:5], off nt
	ds_read_b128 v[2:5], v126 offset:8064
	s_waitcnt lgkmcnt(0)
	global_store_dwordx4 v[6:7], v[2:5], off nt
	s_branch .LBB0_253

; template <int SRC, bool Q8, bool OUTF>
; DI void ln_rows(const void* __restrict__ srcv, const u16* res, u16* dstb, uint32_t* __restrict__ dstq, float* __restrict__ xsc, float* __restrict__ dstf,
;                 const float* __restrict__ g, const float* __restrict__ b, int nrows, const int WAVE_S) {
;     ...
;     if (OUTF) {
;       if (dstf != nullptr) {
; #pragma unroll
;         for (int q = 0; q < 4; ++q) *(f32x4*)(dstf + (size_t)row * DM + 512 * (q >> 1) + 8 * lane + 4 * (q & 1)) = v[q];
;       }
.LBB0_639:
	s_and_b64 vcc, exec, s[44:45]
	s_cbranch_vccz .LBB0_641
	v_lshlrev_b64 v[78:79], 12, v[76:77]
	v_lshl_add_u64 v[78:79], v[72:73], 0, v[78:79]
	global_store_dwordx4 v[78:79], v[34:37], off nt
	global_store_dwordx4 v[78:79], v[38:41], off offset:16 nt
	global_store_dwordx4 v[78:79], v[42:45], off offset:2048 nt
	global_store_dwordx4 v[78:79], v[46:49], off offset:2064 nt

; template <int SRC, bool Q8, bool OUTF>
; DI void ln_rows(const void* __restrict__ srcv, const u16* res, u16* dstb, uint32_t* __restrict__ dstq, float* __restrict__ xsc, float* __restrict__ dstf,
;                 const float* __restrict__ g, const float* __restrict__ b, int nrows, const int WAVE_S) {
;     ...
;     if (OUTF) {
;       if (dstf != nullptr) {
; #pragma unroll
;         for (int q = 0; q < 4; ++q) *(f32x4*)(dstf + (size_t)row * DM + 512 * (q >> 1) + 8 * lane + 4 * (q & 1)) = v[q];
;       }
.LBB0_644:
	s_and_b64 vcc, exec, s[44:45]
	s_mov_b32 s18, 0xffff
	s_cbranch_vccz .LBB0_635
	v_lshlrev_b64 v[76:77], 12, v[74:75]
	v_lshl_add_u64 v[76:77], v[72:73], 0, v[76:77]
	global_store_dwordx4 v[76:77], v[50:53], off nt
	global_store_dwordx4 v[76:77], v[54:57], off offset:16 nt
	global_store_dwordx4 v[76:77], v[58:61], off offset:2048 nt
	global_store_dwordx4 v[76:77], v[62:65], off offset:2064 nt
	s_branch .LBB0_635
